# v19: v16 + attention B Q-fragment copies only when a next task was prefetched; attention A thread-constant unit header computed once per phase; attention A stage-store addresses hoisted
# speedup vs baseline: 1.0115x; 1.0115x over previous
; template <int MIX, bool DRY = false>
; __device__ __forceinline__ void attn_phase(LAS unsigned char* lds, const bf16_t* Qb, const bf16_t* Kb, const bf16_t* Vb, bf16_t* Gb, const float* qg, const float* kg, const float* sinks) {
;     ...
;             for (int task = wave; task < ntask; task += 8) {
;                 TASK_DECODE(task)
;                 const int qi = r, head = kvh * REP + hr;
;                 float M2 = Mb * LOG2E; if (MIX == 0) M2 = fmaxf(Mb, sinks[head]) * LOG2E;
;                 const float negM2 = -M2;
;                 bf16x8 qf[4];
; #pragma unroll
;                 for (int s = 0; s < 4; ++s) qf[s] = qn[s];
;                 if (task + 8 < ntask) { const int t2_ = task + 8; int hr2, tl2;
;                     if (MIX == 0) { hr2 = t2_ >> 1; tl2 = 32 * (t2_ & 1) + r; } else { hr2 = t2_ >> 2; tl2 = 32 * (t2_ & 3) + r; }
;                     const bf16_t* qp_ = Qg + (rowb + t0 + tl2) * 1024 + (kvh * REP + hr2) * 64 + 8 * h;
; #pragma unroll
;                     for (int s = 0; s < 4; ++s) qn[s] = *(const bf16x8*)(qp_ + 16 * s); }
.LBB0_431:
	s_or_b64 exec, exec, s[16:17]
	s_addk_i32 s28, 0x100
	s_and_b64 vcc, exec, s[14:15]
	s_cbranch_vccnz .LBB0_413
	s_waitcnt vmcnt(2)
	v_mov_b64_e32 v[180:181], v[160:161]
	v_mov_b64_e32 v[184:185], v[156:157]
	s_waitcnt vmcnt(1)
	v_mov_b64_e32 v[176:177], v[164:165]
	s_waitcnt vmcnt(0)
	v_mov_b64_e32 v[172:173], v[168:169]
	v_mov_b64_e32 v[178:179], v[158:159]
	v_mov_b64_e32 v[182:183], v[154:155]
	v_mov_b64_e32 v[174:175], v[162:163]
	v_mov_b64_e32 v[170:171], v[166:167]

; template <int MIX, bool DRY = false>
; __device__ __forceinline__ void attn_phase(LAS unsigned char* lds, const bf16_t* Qb, const bf16_t* Kb, const bf16_t* Vb, bf16_t* Gb, const float* qg, const float* kg, const float* sinks) {
;     ...
;                 if (task + 8 < ntask) { const int t2_ = task + 8; int hr2, tl2;
;                     if (MIX == 0) { hr2 = t2_ >> 1; tl2 = 32 * (t2_ & 1) + r; } else { hr2 = t2_ >> 2; tl2 = 32 * (t2_ & 3) + r; }
;                     const bf16_t* qp_ = Qg + (rowb + t0 + tl2) * 1024 + (kvh * REP + hr2) * 64 + 8 * h;
; #pragma unroll
;                     for (int s = 0; s < 4; ++s) qn[s] = *(const bf16x8*)(qp_ + 16 * s); }
.LBB0_436:
	s_add_i32 s29, s29, 8
	s_cmp_ge_i32 s29, s27
	s_cselect_b64 s[14:15], -1, 0
	s_waitcnt vmcnt(0)
	s_and_b64 vcc, exec, s[14:15]
	s_cbranch_vccnz .LBB0_438
	s_and_b32 s34, s28, 0x60
	s_lshr_b32 s17, s29, 2
	v_or_b32_e32 v16, s34, v193
	v_or_b32_e32 v16, s82, v16
	v_mov_b32_e32 v17, s83
	s_add_i32 s17, s17, s23
	v_lshlrev_b64 v[16:17], 11, v[16:17]
	s_lshl_b32 s34, s17, 6
	v_lshl_add_u64 v[16:17], s[10:11], 0, v[16:17]
	s_ashr_i32 s35, s34, 31
	v_lshl_add_u64 v[16:17], s[34:35], 1, v[16:17]
	v_lshl_add_u64 v[16:17], v[16:17], 0, v[112:113]
	global_load_dwordx4 v[154:157], v[16:17], off
	global_load_dwordx4 v[158:161], v[16:17], off offset:32
	global_load_dwordx4 v[162:165], v[16:17], off offset:64
	global_load_dwordx4 v[166:169], v[16:17], off offset:96

; template <int MIX, bool DRY = false>
; __device__ __forceinline__ void attn_phase(LAS unsigned char* lds, const bf16_t* Qb, const bf16_t* Kb, const bf16_t* Vb, bf16_t* Gb, const float* qg, const float* kg, const float* sinks) {
;     ...
;     for (int g = 0; g < NG; ++g) { float mq = fabsf(qg[g * 64 + lane0]), mk = fabsf(kg[g * 64 + lane0]);
; #pragma unroll
;         for (int o = 1; o < 64; o <<= 1) { mq = fmaxf(mq, __shfl_xor(mq, o)); mk = fmaxf(mk, __shfl_xor(mk, o)); }
;         Mb = fmaxf(Mb, 8.0f * mq * mk); }
.LBB0_484:
	s_and_b64 vcc, exec, s[4:5]
	s_cbranch_vccz .LBB0_520
	v_readlane_b32 s4, v251, 50
	v_readlane_b32 s0, v251, 52
	v_readlane_b32 s5, v251, 51
	s_lshl_b32 s0, s0, 6
	s_mov_b32 s1, s5
	v_readlane_b32 s4, v252, 0
	s_lshl_b64 s[0:1], s[0:1], 2
	v_readlane_b32 s10, v252, 6
	v_readlane_b32 s5, v252, 1
	v_readlane_b32 s11, v252, 7
	s_add_u32 s4, s10, s0
	v_mov_b32_e32 v159, v196
	s_mov_b32 s32, 0
	v_ashrrev_i32_e32 v237, 4, v159
	v_lshlrev_b32_e32 v238, 2, v237
	v_and_b32_e32 v238, 4, v238
	v_xor_b32_e32 v237, v237, v159
	v_bitop3_b32 v237, v237, v238, 7 bitop3:0x6c
	v_ashrrev_i32_e32 v238, 3, v159
	v_lshlrev_b32_e32 v238, 7, v238
	v_lshl_or_b32 v237, v237, 4, v238
	v_add_u32_e32 v238, 0x1a800, v237
	v_add_u32_e32 v237, 0x10800, v237
	v_readlane_b32 s12, v252, 8
	s_addc_u32 s5, s11, s1
	v_readlane_b32 s13, v252, 9
	v_and_b32_e32 v0, 63, v159
	s_add_u32 s0, s12, s0
	v_lshlrev_b32_e32 v0, 2, v0
	global_load_dword v1, v0, s[4:5]
	s_addc_u32 s1, s13, s1
	global_load_dword v0, v0, s[0:1]
	v_and_b32_e32 v2, 64, v197
	v_xor_b32_e32 v3, 1, v197
	v_add_u32_e32 v2, 64, v2
	v_cmp_lt_i32_e32 vcc, v3, v2
	v_xor_b32_e32 v4, 2, v197
	v_xor_b32_e32 v5, 4, v197
	v_cndmask_b32_e32 v3, v197, v3, vcc
	v_lshlrev_b32_e32 v3, 2, v3
	v_cmp_lt_i32_e32 vcc, v4, v2
	v_xor_b32_e32 v6, 8, v197
	v_xor_b32_e32 v7, 16, v197
	v_cndmask_b32_e32 v4, v197, v4, vcc
	v_lshlrev_b32_e32 v4, 2, v4
	v_cmp_lt_i32_e32 vcc, v5, v2
	v_xor_b32_e32 v8, 32, v197
	v_readlane_b32 s0, v251, 53
	v_readlane_b32 s1, v251, 54
	v_readlane_b32 s6, v252, 2
	v_readlane_b32 s7, v252, 3
	v_readlane_b32 s8, v252, 4
	v_readlane_b32 s9, v252, 5
	v_readlane_b32 s14, v252, 10
	v_readlane_b32 s15, v252, 11
	v_readlane_b32 s16, v252, 12
	v_readlane_b32 s17, v252, 13
	v_readlane_b32 s18, v252, 14
	v_readlane_b32 s19, v252, 15
	s_waitcnt vmcnt(0)
	v_and_b32_e32 v9, 0x7fffffff, v1
	ds_bpermute_b32 v9, v3, v9
	s_waitcnt vmcnt(0)
	v_and_b32_e32 v10, 0x7fffffff, v0
	ds_bpermute_b32 v3, v3, v10
	v_max_f32_e64 v1, |v1|, |v1|
	v_max_f32_e64 v0, |v0|, |v0|
	s_waitcnt lgkmcnt(1)
	v_max_f32_e32 v9, v9, v9
	v_max_f32_e32 v1, v1, v9
	s_waitcnt lgkmcnt(0)
	v_max_f32_e32 v3, v3, v3
	ds_bpermute_b32 v9, v4, v1
	v_max_f32_e32 v0, v0, v3
	ds_bpermute_b32 v3, v4, v0
	v_cndmask_b32_e32 v4, v197, v5, vcc
	v_lshlrev_b32_e32 v4, 2, v4
	s_waitcnt lgkmcnt(1)
	v_max_f32_e32 v5, v9, v9
	v_max_f32_e32 v1, v1, v5
	s_waitcnt lgkmcnt(0)
	v_max_f32_e32 v3, v3, v3
	ds_bpermute_b32 v5, v4, v1
	v_max_f32_e32 v0, v0, v3
	ds_bpermute_b32 v3, v4, v0
	v_cmp_lt_i32_e32 vcc, v6, v2
	s_waitcnt lgkmcnt(1)
	v_max_f32_e32 v5, v5, v5
	v_cndmask_b32_e32 v4, v197, v6, vcc
	v_lshlrev_b32_e32 v4, 2, v4
	v_max_f32_e32 v1, v1, v5
	s_waitcnt lgkmcnt(0)
	v_max_f32_e32 v3, v3, v3
	ds_bpermute_b32 v5, v4, v1
	v_max_f32_e32 v0, v0, v3
	ds_bpermute_b32 v3, v4, v0
	v_cmp_lt_i32_e32 vcc, v7, v2
	s_waitcnt lgkmcnt(1)
	v_max_f32_e32 v5, v5, v5
	v_cndmask_b32_e32 v4, v197, v7, vcc
	v_lshlrev_b32_e32 v4, 2, v4
	v_max_f32_e32 v1, v1, v5
	s_waitcnt lgkmcnt(0)
	v_max_f32_e32 v3, v3, v3
	ds_bpermute_b32 v5, v4, v1
	v_max_f32_e32 v0, v0, v3
	ds_bpermute_b32 v3, v4, v0
	v_cmp_lt_i32_e32 vcc, v8, v2
	s_nop 1
	v_cndmask_b32_e32 v2, v197, v8, vcc
	v_lshlrev_b32_e32 v164, 2, v2
	s_waitcnt lgkmcnt(1)
	v_max_f32_e32 v2, v5, v5
	v_max_f32_e32 v1, v1, v2
	s_waitcnt lgkmcnt(0)
	v_max_f32_e32 v2, v3, v3
	v_max_f32_e32 v0, v0, v2
	ds_bpermute_b32 v3, v164, v1
	ds_bpermute_b32 v2, v164, v0
	s_and_b64 vcc, exec, s[0:1]
	v_readfirstlane_b32 s0, v159
	s_cbranch_vccnz .LBB0_487
	v_mov_b32_e32 v4, v159
	v_readlane_b32 s4, v253, 58
	v_ashrrev_i32_e32 v12, 3, v4
	v_lshlrev_b32_e32 v4, 4, v4
	v_and_b32_e32 v112, 0x70, v4
	v_readlane_b32 s5, v253, 59
	v_min_i32_e32 v8, 0xbf, v12
	v_readlane_b32 s1, v251, 2
	v_lshl_add_u64 v[4:5], s[4:5], 0, v[112:113]
	v_readlane_b32 s4, v253, 62
	v_readlane_b32 s5, v253, 63
	v_add_u32_e32 v8, s1, v8
	v_ashrrev_i32_e32 v9, 31, v8
	v_lshl_add_u64 v[6:7], s[4:5], 0, v[112:113]
	v_readlane_b32 s4, v251, 0
	v_lshlrev_b64 v[8:9], 7, v[8:9]
	v_readlane_b32 s5, v251, 1
	v_readlane_b32 s1, v251, 4
	s_nop 0
	v_lshl_add_u64 v[8:9], v[8:9], 0, s[4:5]
	v_lshlrev_b64 v[8:9], 1, v[8:9]
	v_lshl_add_u64 v[10:11], v[4:5], 0, v[8:9]
	v_lshl_add_u64 v[8:9], v[6:7], 0, v[8:9]
	global_load_dwordx4 v[114:117], v[10:11], off
	global_load_dwordx4 v[108:111], v[8:9], off
	v_min_i32_e32 v8, 0x7f, v12
	v_add_u32_e32 v8, s1, v8
	v_ashrrev_i32_e32 v9, 31, v8
	v_lshlrev_b64 v[8:9], 7, v[8:9]
	v_lshl_add_u64 v[8:9], v[8:9], 0, s[4:5]
	v_lshlrev_b64 v[8:9], 1, v[8:9]
	v_lshl_add_u64 v[10:11], v[4:5], 0, v[8:9]
	v_lshl_add_u64 v[8:9], v[6:7], 0, v[8:9]
	global_load_dwordx4 v[122:125], v[10:11], off
	global_load_dwordx4 v[118:121], v[8:9], off
	v_min_i32_e32 v8, 63, v12
	v_readlane_b32 s1, v251, 3
	s_nop 1
	v_add_u32_e32 v8, s1, v8
	v_ashrrev_i32_e32 v9, 31, v8
	v_lshlrev_b64 v[8:9], 7, v[8:9]
	v_lshl_add_u64 v[8:9], v[8:9], 0, s[4:5]
	v_lshlrev_b64 v[8:9], 1, v[8:9]
	v_lshl_add_u64 v[4:5], v[4:5], 0, v[8:9]
	v_lshl_add_u64 v[6:7], v[6:7], 0, v[8:9]
	global_load_dwordx4 v[130:133], v[4:5], off
	global_load_dwordx4 v[126:129], v[6:7], off

; template <int MIX, bool DRY = false>
; __device__ __forceinline__ void attn_phase(LAS unsigned char* lds, const bf16_t* Qb, const bf16_t* Kb, const bf16_t* Vb, bf16_t* Gb, const float* qg, const float* kg, const float* sinks) {
;     ...
;             bf16x8 qn[4];
;             { TASK_DECODE(wave) (void)f0; (void)tb0; const bf16_t* qp_ = Qg + (rowb + t0 + tl) * 1024 + (kvh * REP + hr) * 64 + 8 * h;
; #pragma unroll
;               for (int s = 0; s < 4; ++s) qn[s] = *(const bf16x8*)(qp_ + 16 * s); }
;             if (!(PRE0 && st == 0)) {
;                 __syncthreads();
;                 STAGE_STORE(st)
;             }
.LBB0_494:
	s_ashr_i32 s5, s4, 31
	s_lshr_b32 s8, s5, 26
	s_add_i32 s8, s4, s8
	s_and_b32 s10, s8, 0x3ffffc0
	s_lshr_b32 s5, s5, 25
	s_ashr_i32 s9, s8, 6
	s_sub_i32 s10, s4, s10
	s_lshr_b32 s8, s8, 31
	s_add_i32 s4, s4, s5
	s_add_i32 s8, s9, s8
	s_ashr_i32 s4, s4, 7
	s_and_b32 s8, s8, 0x1ffffffe
	s_lshl_b32 s22, s10, 6
	s_ashr_i32 s5, s4, 31
	s_sub_i32 s8, s9, s8
	s_lshl_b64 s[4:5], s[4:5], 12
	s_ashr_i32 s9, s22, 31
	v_and_b32_e32 v166, 31, v0
	s_add_u32 s19, s4, s22
	v_or_b32_e32 v2, s17, v166
	s_addc_u32 s20, s5, s9
	v_or_b32_e32 v2, s19, v2
	v_mov_b32_e32 v3, s20
	v_readlane_b32 s4, v252, 22
	v_lshlrev_b64 v[2:3], 11, v[2:3]
	v_readlane_b32 s5, v252, 23
	s_lshl_b32 s21, s8, 3
	v_bfe_u32 v1, v0, 5, 1
	v_lshl_add_u64 v[2:3], s[4:5], 0, v[2:3]
	s_add_i32 s4, s21, s15
	s_lshl_b32 s4, s4, 6
	s_ashr_i32 s5, s4, 31
	v_lshl_add_u64 v[2:3], s[4:5], 1, v[2:3]
	v_lshlrev_b32_e32 v112, 4, v1
	v_lshl_add_u64 v[2:3], v[2:3], 0, v[112:113]
	global_load_dwordx4 v[154:157], v[2:3], off
	global_load_dwordx4 v[104:107], v[2:3], off offset:32
	global_load_dwordx4 v[150:153], v[2:3], off offset:64
	global_load_dwordx4 v[80:83], v[2:3], off offset:96
	s_barrier
	s_waitcnt vmcnt(9)
	ds_write_b128 v237, v[114:117]
	s_waitcnt vmcnt(8)
	ds_write_b128 v238, v[108:111]
	s_waitcnt vmcnt(7)
	ds_write_b128 v237, v[122:125] offset:8192
	s_waitcnt vmcnt(6)
	ds_write_b128 v238, v[118:121] offset:8192
	s_waitcnt vmcnt(5)
	ds_write_b128 v237, v[130:133] offset:16384
	s_waitcnt vmcnt(4)
	ds_write_b128 v238, v[126:129] offset:16384

; template <int MIX, bool DRY = false>
; __device__ __forceinline__ void attn_phase(LAS unsigned char* lds, const bf16_t* Qb, const bf16_t* Kb, const bf16_t* Vb, bf16_t* Gb, const float* qg, const float* kg, const float* sinks) {
;     ...
;         const int lane = tidu & 63, r = lane & 31, h = lane >> 5;
;     const bf16x8 ones8 = {0x3F80, 0x3F80, 0x3F80, 0x3F80, 0x3F80, 0x3F80, 0x3F80, 0x3F80};
;     const int trq = (lane & 15) >> 2, trp = lane & 3, trg = (lane >> 4) & 1;
;     int koff[4];
; #pragma unroll
;     for (int s = 0; s < 4; ++s) koff[s] = r * 128 + (((2 * s + h) ^ ST_SW(r)) << 4);
;     const int vrl = 4 * h + trq, vrh = vrl + 8;
;     const int voff0 = vrl * 128 + (((2 * trg + (trp >> 1)) ^ ST_SW(vrl)) << 4) + 8 * (trp & 1);
;     const int voff1 = vrl * 128 + (((4 + 2 * trg + (trp >> 1)) ^ ST_SW(vrl)) << 4) + 8 * (trp & 1);
;     const int voff0h = vrh * 128 + (((2 * trg + (trp >> 1)) ^ ST_SW(vrh)) << 4) + 8 * (trp & 1);
;     const int voff1h = vrh * 128 + (((4 + 2 * trg + (trp >> 1)) ^ ST_SW(vrh)) << 4) + 8 * (trp & 1);
;     const int vkey = lane >> 3, vchunk = lane & 7;
;     const int tr_lo = (4 * h + trq) * VW_ROW + (16 * trg + 4 * trp) * 2, tr_hi = tr_lo + 8 * VW_ROW;
;     const int lrow = tidu >> 3, lchunk = tidu & 7;
;     ...
;             for (int task = wave; task < ntask; task += 8) {
;                 TASK_DECODE(task)
;                 const int qi = r, head = kvh * REP + hr;
;                 float M2 = Mb * LOG2E; if (MIX == 0) M2 = fmaxf(Mb, sinks[head]) * LOG2E;
;                 const float negM2 = -M2;
;                 bf16x8 qf[4];
; #pragma unroll
;                 for (int s = 0; s < 4; ++s) qf[s] = qn[s];
.LBB0_502:
	s_andn2_b64 vcc, exec, s[0:1]
	s_cbranch_vccnz .LBB0_489
	s_cmp_lg_u32 s32, 0
	s_cbranch_scc1 .LhdrA_skip
	v_bfe_u32 v5, v166, 1, 3
	v_lshlrev_b32_e32 v6, 1, v166
	v_bitop3_b32 v5, v6, v5, 4 bitop3:0x6c
	v_xor_b32_e32 v6, v5, v1
	v_lshlrev_b32_e32 v169, 4, v6
	v_or_b32_e32 v6, 2, v1
	v_xor_b32_e32 v6, v5, v6
	v_lshlrev_b32_e32 v2, 3, v1
	v_lshlrev_b32_e32 v158, 2, v1
	v_lshlrev_b32_e32 v170, 4, v6
	v_or_b32_e32 v6, 4, v1
	v_or_b32_e32 v1, 6, v1
	v_lshrrev_b32_e32 v4, 2, v0
	v_xor_b32_e32 v6, v5, v6
	v_xor_b32_e32 v1, v5, v1
	v_lshrrev_b32_e32 v5, 3, v0
	v_bfe_u32 v7, v0, 1, 1
	v_lshlrev_b32_e32 v171, 4, v6
	v_lshlrev_b32_e32 v172, 4, v1
	v_and_or_b32 v1, v4, 3, v158
	v_lshrrev_b32_e32 v6, 1, v0
	v_and_or_b32 v5, v5, 2, v7
	v_lshlrev_b32_e32 v0, 3, v0
	v_or_b32_e32 v4, 8, v1
	v_lshlrev_b32_e32 v173, 7, v1
	v_lshrrev_b32_e32 v1, 1, v1
	v_and_b32_e32 v7, 4, v6
	v_and_b32_e32 v175, 8, v0
	v_or_b32_e32 v0, 4, v5
	v_bitop3_b32 v8, v7, v5, v1 bitop3:0x36
	v_bitop3_b32 v1, v7, v0, v1 bitop3:0x36
	v_lshlrev_b32_e32 v176, 4, v1
	v_lshrrev_b32_e32 v1, 1, v4
	v_bitop3_b32 v1, v6, v1, 4 bitop3:0x6c
	v_sub_u32_e32 v3, v166, v158
	v_lshlrev_b32_e32 v177, 7, v4
	v_xor_b32_e32 v4, v1, v5
	v_xor_b32_e32 v0, v1, v0
	v_add_u32_e32 v167, 1, v166
	v_lshlrev_b32_e32 v168, 7, v166
	v_lshlrev_b32_e32 v174, 4, v8
	v_lshlrev_b32_e32 v178, 4, v4
	v_lshlrev_b32_e32 v179, 4, v0
	v_subrev_u32_e32 v180, 31, v166
	v_cmp_gt_i32_e64 s[36:37], 0, v3
	v_cmp_gt_i32_e64 s[38:39], 1, v3
	v_cmp_gt_i32_e64 s[40:41], 2, v3
	v_cmp_gt_i32_e64 s[42:43], 3, v3
	v_cmp_gt_i32_e64 s[44:45], 8, v3
	v_cmp_gt_i32_e64 s[46:47], 9, v3
	v_cmp_gt_i32_e64 s[48:49], 10, v3
	v_cmp_gt_i32_e64 s[50:51], 11, v3
	v_cmp_gt_i32_e64 s[52:53], 16, v3
	v_cmp_gt_i32_e64 s[54:55], 17, v3
	v_cmp_gt_i32_e64 s[56:57], 18, v3
	v_cmp_gt_i32_e64 s[58:59], 19, v3
	v_cmp_gt_i32_e64 s[60:61], 24, v3
	v_cmp_gt_i32_e64 s[62:63], 25, v3
	v_cmp_gt_i32_e64 s[64:65], 26, v3
	v_cmp_gt_i32_e64 s[66:67], 27, v3
	v_lshlrev_b32_e32 v160, 1, v2
	s_mov_b32 s32, 1
.LhdrA_skip:
	s_waitcnt vmcnt(2)
	v_mov_b64_e32 v[136:137], v[106:107]
	v_mov_b64_e32 v[138:139], v[154:155]
	s_waitcnt vmcnt(1)
	v_mov_b64_e32 v[142:143], v[150:151]
	s_waitcnt vmcnt(0)
	v_mov_b64_e32 v[148:149], v[82:83]
	s_addk_i32 s22, 0xff80
	v_lshlrev_b32_e32 v112, 1, v158
	s_mov_b32 s23, s16
	s_mov_b32 s9, s14
	v_mov_b64_e32 v[134:135], v[104:105]
	v_mov_b64_e32 v[140:141], v[156:157]
	v_mov_b64_e32 v[144:145], v[152:153]
	v_mov_b64_e32 v[146:147], v[80:81]
	s_branch .LBB0_505
